# v91: v90 with the XCD-local seams guarded by the launch census flag (full barrier otherwise) and the second conversion register set moved to v84-v139
# speedup vs baseline: 1.0036x; 1.0009x over previous
; __device__ __forceinline__ unsigned xb_add(unsigned* p, unsigned v) { return __hip_atomic_fetch_add(p, v, __ATOMIC_RELAXED, __HIP_MEMORY_SCOPE_AGENT); }
; __device__ __forceinline__ void xcd_barrier(const XcdBarrier& b) {
;     ...
;     if (threadIdx.x == 0) {
;         unsigned* bar = b.bar;
;         __builtin_amdgcn_s_waitcnt(0);
;         unsigned nloc = b.st[0], nx = b.st[1];
;         if (nloc == 0u) { xcd_barrier_complete(bar, b.x, nloc, nx); b.st[0] = nloc; b.st[1] = nx; }
;         const unsigned old = xb_add(&bar[XB_XSUB(b.x)], 1u);
;         const unsigned gen = old / nloc;
;         if (old + 1u == (gen + 1u) * nloc) {
;             __builtin_amdgcn_fence(__ATOMIC_RELEASE, "agent");
;             asm volatile("s_waitcnt vmcnt(0)" ::: "memory");
;             const unsigned og = xb_add(&bar[XB_TOP], 1u);
;             const unsigned tg = og / nx;
;             if (og + 1u == (tg + 1u) * nx) xb_add(&bar[XB_TOPGEN], 1u);
.LBB0_635:
	s_andn2_saveexec_b64 s[2:3], s[10:11]
	s_cbranch_execz .LBB0_655
	s_mov_b64 s[10:11], exec
	s_waitcnt lgkmcnt(0)
	v_mov_b32_e32 v3, 0x20188
	ds_read_b32 v3, v3
	s_waitcnt lgkmcnt(0)
	v_readfirstlane_b32 s0, v3
	s_cmp_lg_u32 s0, 0
	s_cbranch_scc1 .Lxloc_out
	buffer_wbl2 sc1
	s_waitcnt lgkmcnt(0)
	s_waitcnt vmcnt(0)
	v_mbcnt_lo_u32_b32 v3, s10, 0
	v_mbcnt_hi_u32_b32 v3, s11, v3
	v_cmp_eq_u32_e32 vcc, 0, v3
	s_and_saveexec_b64 s[12:13], vcc
	s_cbranch_execz .LBB0_638
	s_bcnt1_i32_b64 s0, s[10:11]
	v_mov_b32_e32 v4, s0
	v_mov_b32_e32 v5, 0x7000
	global_atomic_add v4, v5, v4, s[6:7] offset:1024 sc0

; __device__ __forceinline__ unsigned xb_add(unsigned* p, unsigned v) { return __hip_atomic_fetch_add(p, v, __ATOMIC_RELAXED, __HIP_MEMORY_SCOPE_AGENT); }
; __device__ __forceinline__ void xcd_barrier(const XcdBarrier& b) {
;     ...
;             __builtin_amdgcn_fence(__ATOMIC_ACQUIRE, "agent");
;             xb_add(&bar[XB_XGEN(b.x)], 1u);
;             asm volatile("s_waitcnt vmcnt(0)" ::: "memory");
.Lxloc_out:
	s_mov_b64 s[6:7], exec
	v_mbcnt_lo_u32_b32 v2, s6, 0
	v_mbcnt_hi_u32_b32 v2, s7, v2
	v_cmp_eq_u32_e32 vcc, 0, v2
	s_waitcnt vmcnt(0)
	buffer_inv sc1
	s_and_saveexec_b64 s[10:11], vcc
	s_cbranch_execz .LBB0_654
	s_bcnt1_i32_b64 s0, s[6:7]
	v_mov_b32_e32 v2, s0
	v_mov_b32_e32 v3, 0x2000
	global_atomic_add v3, v2, s[8:9] offset:1024

; __device__ __forceinline__ unsigned xb_add(unsigned* p, unsigned v) { return __hip_atomic_fetch_add(p, v, __ATOMIC_RELAXED, __HIP_MEMORY_SCOPE_AGENT); }
; __device__ __forceinline__ void xcd_barrier(const XcdBarrier& b) {
;     ...
;     if (threadIdx.x == 0) {
;         unsigned* bar = b.bar;
;         __builtin_amdgcn_s_waitcnt(0);
;         unsigned nloc = b.st[0], nx = b.st[1];
;         if (nloc == 0u) { xcd_barrier_complete(bar, b.x, nloc, nx); b.st[0] = nloc; b.st[1] = nx; }
;         const unsigned old = xb_add(&bar[XB_XSUB(b.x)], 1u);
;         const unsigned gen = old / nloc;
;         if (old + 1u == (gen + 1u) * nloc) {
;             __builtin_amdgcn_fence(__ATOMIC_RELEASE, "agent");
;             asm volatile("s_waitcnt vmcnt(0)" ::: "memory");
;             const unsigned og = xb_add(&bar[XB_TOP], 1u);
;             const unsigned tg = og / nx;
;             if (og + 1u == (tg + 1u) * nx) xb_add(&bar[XB_TOPGEN], 1u);
.LBB0_718:
	s_andn2_saveexec_b64 s[2:3], s[10:11]
	s_cbranch_execz .LBB0_738
	s_mov_b64 s[10:11], exec
	s_waitcnt lgkmcnt(0)
	v_mov_b32_e32 v3, 0x20188
	ds_read_b32 v3, v3
	s_waitcnt lgkmcnt(0)
	v_readfirstlane_b32 s1, v3
	s_cmp_lg_u32 s1, 0
	s_cbranch_scc1 .Lxloc_up
	buffer_wbl2 sc1
	s_waitcnt lgkmcnt(0)
	s_waitcnt vmcnt(0)
	v_mbcnt_lo_u32_b32 v3, s10, 0
	v_mbcnt_hi_u32_b32 v3, s11, v3
	v_cmp_eq_u32_e32 vcc, 0, v3
	s_and_saveexec_b64 s[12:13], vcc
	s_cbranch_execz .LBB0_721
	s_bcnt1_i32_b64 s1, s[10:11]
	v_mov_b32_e32 v4, s1
	v_mov_b32_e32 v5, 0x7000
	global_atomic_add v4, v5, v4, s[6:7] offset:1024 sc0

; __device__ __forceinline__ unsigned xb_add(unsigned* p, unsigned v) { return __hip_atomic_fetch_add(p, v, __ATOMIC_RELAXED, __HIP_MEMORY_SCOPE_AGENT); }
; __device__ __forceinline__ void xcd_barrier(const XcdBarrier& b) {
;     ...
;             __builtin_amdgcn_fence(__ATOMIC_ACQUIRE, "agent");
;             xb_add(&bar[XB_XGEN(b.x)], 1u);
;             asm volatile("s_waitcnt vmcnt(0)" ::: "memory");
.Lxloc_up:
	s_mov_b64 s[6:7], exec
	v_mbcnt_lo_u32_b32 v2, s6, 0
	v_mbcnt_hi_u32_b32 v2, s7, v2
	v_cmp_eq_u32_e32 vcc, 0, v2
	s_waitcnt vmcnt(0)
	buffer_inv sc1
	s_and_saveexec_b64 s[10:11], vcc
	s_cbranch_execz .LBB0_737
	s_bcnt1_i32_b64 s1, s[6:7]
	v_mov_b32_e32 v2, s1
	v_mov_b32_e32 v3, 0x2000
	global_atomic_add v3, v2, s[8:9] offset:1024

; __device__ __forceinline__ unsigned xb_add(unsigned* p, unsigned v) { return __hip_atomic_fetch_add(p, v, __ATOMIC_RELAXED, __HIP_MEMORY_SCOPE_AGENT); }
; __device__ __forceinline__ void xcd_barrier(const XcdBarrier& b) {
;     ...
;     if (threadIdx.x == 0) {
;         unsigned* bar = b.bar;
;         __builtin_amdgcn_s_waitcnt(0);
;         unsigned nloc = b.st[0], nx = b.st[1];
;         if (nloc == 0u) { xcd_barrier_complete(bar, b.x, nloc, nx); b.st[0] = nloc; b.st[1] = nx; }
;         const unsigned old = xb_add(&bar[XB_XSUB(b.x)], 1u);
;         const unsigned gen = old / nloc;
;         if (old + 1u == (gen + 1u) * nloc) {
;             __builtin_amdgcn_fence(__ATOMIC_RELEASE, "agent");
;             asm volatile("s_waitcnt vmcnt(0)" ::: "memory");
;             const unsigned og = xb_add(&bar[XB_TOP], 1u);
;             const unsigned tg = og / nx;
;             if (og + 1u == (tg + 1u) * nx) xb_add(&bar[XB_TOPGEN], 1u);
.LBB0_817:
	s_andn2_saveexec_b64 s[0:1], s[8:9]
	s_cbranch_execz .LBB0_268
	s_mov_b64 s[8:9], exec
	s_waitcnt lgkmcnt(0)
	v_mov_b32_e32 v3, 0x20188
	ds_read_b32 v3, v3
	s_waitcnt lgkmcnt(0)
	v_readfirstlane_b32 s0, v3
	s_cmp_lg_u32 s0, 0
	s_cselect_b32 s0, 1, 0
	s_cmp_eq_u32 s71, 0
	s_cselect_b32 s0, s0, 0
	s_cmp_lg_u32 s0, 0
	s_cbranch_scc1 .Lxloc_down
	buffer_wbl2 sc1
	s_waitcnt lgkmcnt(0)
	s_waitcnt vmcnt(0)
	v_mbcnt_lo_u32_b32 v3, s8, 0
	v_mbcnt_hi_u32_b32 v3, s9, v3
	v_cmp_eq_u32_e32 vcc, 0, v3
	s_and_saveexec_b64 s[10:11], vcc
	s_cbranch_execz .LBB0_820
	s_bcnt1_i32_b64 s0, s[8:9]
	v_mov_b32_e32 v4, s0
	v_mov_b32_e32 v5, 0x7000
	global_atomic_add v4, v5, v4, s[4:5] offset:1024 sc0
